# one static s_setprio 1 at kernel entry for the FIRST workgroup on each CU (LDS base == 0), mirror of the previous variant
# speedup vs baseline: 1.0048x; 1.0048x over previous
_Z11mega_kernel6Params:
	v_and_b32_e32 v179, 0x3ff, v0
	s_getreg_b32 s100, hwreg(HW_REG_LDS_ALLOC, 0, 8)
	s_cmp_eq_u32 s100, 0
	s_cbranch_scc0 .Lprio_done
	s_setprio 1
